# grid barrier: workgroups that are not their XCD's last arriver poll the cross-XCD generation word directly instead of waiting for the per-XCD release (one hop less per barrier)
# speedup vs baseline: 1.0937x; 1.0012x over previous
.LBB0_56:
	s_or_b64 exec, exec, s[6:7]
	v_cvt_f32_u32_e32 v5, v3
	s_waitcnt vmcnt(0)
	v_readfirstlane_b32 s4, v4
	v_sub_u32_e32 v4, 0, v3
	v_rcp_iflag_f32_e32 v5, v5
	v_add_u32_e32 v6, s4, v2
	v_mul_f32_e32 v5, 0x4f7ffffe, v5
	v_cvt_u32_f32_e32 v5, v5
	v_mul_lo_u32 v2, v4, v5
	v_mul_hi_u32 v2, v5, v2
	v_add_u32_e32 v2, v5, v2
	v_mul_hi_u32 v2, v6, v2
	v_mul_lo_u32 v4, v2, v3
	v_sub_u32_e32 v4, v6, v4
	v_add_u32_e32 v5, 1, v2
	v_cmp_ge_u32_e32 vcc, v4, v3
	s_nop 1
	v_cndmask_b32_e32 v2, v2, v5, vcc
	v_sub_u32_e32 v5, v4, v3
	v_cndmask_b32_e32 v4, v4, v5, vcc
	v_add_u32_e32 v5, 1, v2
	v_cmp_ge_u32_e32 vcc, v4, v3
	v_add_u32_e32 v4, 1, v6
	s_nop 0
	v_cndmask_b32_e32 v2, v2, v5, vcc
	v_mul_lo_u32 v5, v3, v2
	v_add_u32_e32 v3, v5, v3
	v_cmp_ne_u32_e32 vcc, v4, v3
	s_and_saveexec_b64 s[4:5], vcc
	s_xor_b64 s[4:5], exec, s[4:5]
	s_cbranch_execz .LBB0_70
	s_waitcnt lgkmcnt(0)
	s_add_u32 s10, s98, 0x7500
	s_addc_u32 s11, s99, 0
	v_mov_b32_e32 v1, 0
	global_load_dword v1, v1, s[10:11] sc1
	s_waitcnt vmcnt(0)
	v_cmp_eq_u32_e32 vcc, v1, v2
	s_and_saveexec_b64 s[6:7], vcc
	s_cbranch_execz .LBB0_69
	s_add_u32 s8, s98, 0x4200
	s_addc_u32 s9, s99, 0
	s_mov_b32 s22, 1
	s_mov_b64 s[12:13], 0
	v_mov_b32_e32 v1, 0
	s_branch .LBB0_60
